# P4: no static priority raise for waves 4-7 (after moving the K2 staging to them the two wave classes are balanced without it)
# speedup vs baseline: 1.0074x; 1.0074x over previous
; #define PHASE_IDS() const int tid = otid(), lane = tid & 63, wave = __builtin_amdgcn_readfirstlane(tid >> 6); const int gw = bid * NWAVES + wave; const int gt = bid * NTHREADS + tid; (void)gw; (void)gt; (void)lane; PTRS()
; __global__ void __launch_bounds__(NTHREADS) mega(Args a) {
;     ...
;         { PHASE_IDS();
;         if (wave >= 4) __builtin_amdgcn_s_setprio(1);
;         for (int ui = bid; ui < 5 * 512; ui += G) {
;             const int kind = ui >> 9, idx = ui & 511;
.LBB0_795:
	s_or_b64 exec, exec, s[6:7]
	v_mov_b32_e32 v171, v238
	s_mov_b64 s[0:1], s[86:87]
	s_waitcnt lgkmcnt(0)
	s_barrier
	s_load_dwordx2 s[14:15], s[0:1], 0x98
	s_load_dwordx2 s[16:17], s[0:1], 0x40
	v_readfirstlane_b32 s0, v171
	s_ashr_i32 s0, s0, 6
	s_cmp_gt_i32 s0, 3
	s_cbranch_scc0 .LBB0_797
	s_setprio 0
